# work-queue claim-ahead with a counted wait (vmcnt(8)) so wave 0 does not wait for the previous item's store acks
# baseline (speedup 1.0000x reference)
.LBB0_86:
	ds_read_b128 v[4:7], v3
	v_add_u32_e32 v10, s14, v2
	v_add_u32_e32 v8, 0x80, v10
	v_ashrrev_i32_e32 v9, 31, v8
	s_add_i32 s14, s14, 64
	s_waitcnt lgkmcnt(0)
	v_cvt_pk_bf16_f32 v4, v4, v5
	v_cvt_pk_bf16_f32 v5, v6, v7
	v_lshlrev_b64 v[6:7], 11, v[8:9]
	v_lshl_add_u64 v[6:7], v[0:1], 0, v[6:7]
	global_store_dwordx2 v[6:7], v[4:5], off offset:256
	ds_read_b128 v[4:7], v3 offset:16640
	v_add_u32_e32 v8, 0x90, v10
	v_ashrrev_i32_e32 v9, 31, v8
	s_cmpk_lg_i32 s14, 0x80
	s_waitcnt lgkmcnt(0)
	v_cvt_pk_bf16_f32 v4, v4, v5
	v_cvt_pk_bf16_f32 v5, v6, v7
	v_lshlrev_b64 v[6:7], 11, v[8:9]
	v_lshl_add_u64 v[6:7], v[0:1], 0, v[6:7]
	global_store_dwordx2 v[6:7], v[4:5], off offset:256
	ds_read_b128 v[4:7], v3 offset:33280
	v_add_u32_e32 v8, 0xa0, v10
	v_ashrrev_i32_e32 v9, 31, v8
	s_waitcnt lgkmcnt(0)
	v_cvt_pk_bf16_f32 v4, v4, v5
	v_cvt_pk_bf16_f32 v5, v6, v7
	v_lshlrev_b64 v[6:7], 11, v[8:9]
	v_lshl_add_u64 v[6:7], v[0:1], 0, v[6:7]
	global_store_dwordx2 v[6:7], v[4:5], off offset:256
	ds_read_b128 v[4:7], v3 offset:49920
	v_add_u32_e32 v8, 0xb0, v10
	v_ashrrev_i32_e32 v9, 31, v8
	v_add_u32_e32 v3, 0x10400, v3
	s_waitcnt lgkmcnt(0)
	v_cvt_pk_bf16_f32 v4, v4, v5
	v_cvt_pk_bf16_f32 v5, v6, v7
	v_lshlrev_b64 v[6:7], 11, v[8:9]
	v_lshl_add_u64 v[6:7], v[0:1], 0, v[6:7]
	global_store_dwordx2 v[6:7], v[4:5], off offset:256
	s_cbranch_scc1 .LBB0_86
	s_barrier
	s_branch .LBB0_71
	s_nop 0
	s_nop 0
	s_nop 0
	s_nop 0
	s_nop 0
	s_nop 0
.LBB0_88:
	s_mov_b32 s84, 0
	s_mov_b32 s86, 0
	s_mov_b32 s54, 0
	s_mov_b32 s62, 0
	v_readlane_b32 s56, v255, 36
	s_mov_b64 s[14:15], 0
	s_mov_b32 s65, 0xffff
	s_mov_b32 s85, 0x40280000
	s_mov_b32 s87, 0x40340000
	s_mov_b32 s55, 0x40450000
	s_mov_b32 s63, 0x40710000
	v_readlane_b32 s57, v255, 37

.LBB0_104:
	s_movk_i32 s60, 0x140
	s_andn2_b64 vcc, exec, s[56:57]
	s_cbranch_vccnz .LBB0_201
	v_readlane_b32 s14, v254, 5
	v_readlane_b32 s15, v254, 6
	s_lshl_b32 s14, s14, 6
	s_ashr_i32 s15, s14, 31
	s_lshl_b64 s[14:15], s[14:15], 2
	s_add_u32 s88, s74, s14
	s_addc_u32 s89, s75, s15
	s_add_u32 s14, s74, 0x1c0000
	s_addc_u32 s15, s75, 0
	s_add_u32 s48, s74, 0x1c8000
	s_addc_u32 s49, s75, 0
	v_writelane_b32 v255, s14, 36
	s_add_u32 s44, s74, 0x1a0000
	s_addc_u32 s45, s75, 0
	v_writelane_b32 v255, s15, 37
	s_add_u32 s94, s74, 0x1a8000
	v_readlane_b32 s14, v255, 26
	v_cmp_eq_u32_e64 s[40:41], 0, v192
	s_addc_u32 s95, s75, 0
	s_lshl_b32 s61, s14, 6
	v_readlane_b32 s15, v255, 27
	s_and_saveexec_b64 s[14:15], s[40:41]
	v_mov_b32_e32 v250, 1
	global_atomic_add v251, v169, v250, s[88:89] offset:256 sc0
	s_waitcnt vmcnt(0)
	s_or_b64 exec, exec, s[14:15]
	s_branch .LBB0_108

.LBB0_108:
	s_and_saveexec_b64 s[14:15], s[40:41]
	s_cbranch_execz .LBB0_112
	s_mov_b64 s[18:19], exec
	s_waitcnt vmcnt(7)
	v_mbcnt_lo_u32_b32 v0, s18, 0
	v_mbcnt_hi_u32_b32 v0, s19, v0
	v_cmp_eq_u32_e32 vcc, 0, v0
	s_and_saveexec_b64 s[16:17], vcc
	s_cbranch_execz .LBB0_111
	s_bcnt1_i32_b64 s5, s[18:19]
	s_waitcnt vmcnt(8)
	v_mov_b32_e32 v1, v251
	v_mov_b32_e32 v250, s5
	global_atomic_add v251, v169, v250, s[88:89] offset:256 sc0
